# GEMM mainloops (5 of 7): software-pipelined LDS fragment reads (5 A bufs, 2x2 W bufs) + next-tile global loads hoisted into the MFMA block
# speedup vs baseline: 1.0384x; 1.0384x over previous
.LBB0_20:
	s_waitcnt lgkmcnt(0)
	s_barrier
	s_setprio 2
	ds_read_b128 v[190:193], v179 offset:36864
	ds_read_b128 v[194:197], v179 offset:41472
	ds_read_b128 v[206:209], v178
	ds_read_b128 v[216:219], v178 offset:4608
	ds_read_b128 v[236:239], v178 offset:9216
	ds_read_b128 v[240:243], v178 offset:13824
	ds_read_b128 v[244:247], v178 offset:32
	s_waitcnt lgkmcnt(4)
	v_mfma_f32_32x32x16_bf16 v[114:129], v[190:193], v[206:209], v[114:129]
	v_mfma_f32_32x32x16_bf16 v[98:113], v[194:197], v[206:209], v[98:113]
	ds_read_b128 v[206:209], v178 offset:4640
	ds_read_b128 v[198:201], v179 offset:36896
	ds_read_b128 v[202:205], v179 offset:41504
	s_waitcnt lgkmcnt(6)
	v_mfma_f32_32x32x16_bf16 v[82:97], v[190:193], v[216:219], v[82:97]
	v_mfma_f32_32x32x16_bf16 v[66:81], v[194:197], v[216:219], v[66:81]
	ds_read_b128 v[216:219], v178 offset:9248
	s_waitcnt lgkmcnt(6)
	v_mfma_f32_32x32x16_bf16 v[50:65], v[190:193], v[236:239], v[50:65]
	v_mfma_f32_32x32x16_bf16 v[34:49], v[194:197], v[236:239], v[34:49]
	ds_read_b128 v[236:239], v178 offset:13856
	s_waitcnt lgkmcnt(6)
	v_mfma_f32_32x32x16_bf16 v[18:33], v[190:193], v[240:243], v[18:33]
	v_mfma_f32_32x32x16_bf16 v[2:17], v[194:197], v[240:243], v[2:17]
	ds_read_b128 v[240:243], v178 offset:64
	s_waitcnt lgkmcnt(3)
	v_mfma_f32_32x32x16_bf16 v[114:129], v[198:201], v[244:247], v[114:129]
	v_mfma_f32_32x32x16_bf16 v[98:113], v[202:205], v[244:247], v[98:113]
	ds_read_b128 v[244:247], v178 offset:4672
	ds_read_b128 v[190:193], v179 offset:36928
	ds_read_b128 v[194:197], v179 offset:41536
	v_mfma_f32_32x32x16_bf16 v[82:97], v[198:201], v[206:209], v[82:97]
	v_mfma_f32_32x32x16_bf16 v[66:81], v[202:205], v[206:209], v[66:81]
	ds_read_b128 v[206:209], v178 offset:9280
	s_waitcnt lgkmcnt(6)
	v_mfma_f32_32x32x16_bf16 v[50:65], v[198:201], v[216:219], v[50:65]
	v_mfma_f32_32x32x16_bf16 v[34:49], v[202:205], v[216:219], v[34:49]
	ds_read_b128 v[216:219], v178 offset:13888
	s_waitcnt lgkmcnt(6)
	v_mfma_f32_32x32x16_bf16 v[18:33], v[198:201], v[236:239], v[18:33]
	v_mfma_f32_32x32x16_bf16 v[2:17], v[202:205], v[236:239], v[2:17]
	ds_read_b128 v[236:239], v178 offset:96
	s_waitcnt lgkmcnt(3)
	v_mfma_f32_32x32x16_bf16 v[114:129], v[190:193], v[240:243], v[114:129]
	v_mfma_f32_32x32x16_bf16 v[98:113], v[194:197], v[240:243], v[98:113]
	ds_read_b128 v[240:243], v178 offset:4704
	ds_read_b128 v[198:201], v179 offset:36960
	ds_read_b128 v[202:205], v179 offset:41568
	v_mfma_f32_32x32x16_bf16 v[82:97], v[190:193], v[244:247], v[82:97]
	v_mfma_f32_32x32x16_bf16 v[66:81], v[194:197], v[244:247], v[66:81]
	ds_read_b128 v[244:247], v178 offset:9312
	s_waitcnt lgkmcnt(6)
	v_mfma_f32_32x32x16_bf16 v[50:65], v[190:193], v[206:209], v[50:65]
	v_mfma_f32_32x32x16_bf16 v[34:49], v[194:197], v[206:209], v[34:49]
	ds_read_b128 v[206:209], v178 offset:13920
	s_waitcnt lgkmcnt(6)
	v_mfma_f32_32x32x16_bf16 v[18:33], v[190:193], v[216:219], v[18:33]
	v_mfma_f32_32x32x16_bf16 v[2:17], v[194:197], v[216:219], v[2:17]
	s_waitcnt lgkmcnt(2)
	v_mfma_f32_32x32x16_bf16 v[114:129], v[198:201], v[236:239], v[114:129]
	v_mfma_f32_32x32x16_bf16 v[98:113], v[202:205], v[236:239], v[98:113]
	v_mfma_f32_32x32x16_bf16 v[82:97], v[198:201], v[240:243], v[82:97]
	v_mfma_f32_32x32x16_bf16 v[66:81], v[202:205], v[240:243], v[66:81]
	s_waitcnt lgkmcnt(1)
	v_mfma_f32_32x32x16_bf16 v[50:65], v[198:201], v[244:247], v[50:65]
	v_mfma_f32_32x32x16_bf16 v[34:49], v[202:205], v[244:247], v[34:49]
	s_waitcnt lgkmcnt(0)
	v_mfma_f32_32x32x16_bf16 v[18:33], v[198:201], v[206:209], v[18:33]
	v_mfma_f32_32x32x16_bf16 v[2:17], v[202:205], v[206:209], v[2:17]
	s_setprio 0
.Ltail_20:
	s_add_i32 s3, s3, 1
	s_cmp_lg_u32 s3, 44
	s_cbranch_scc0 .LBB0_26
	s_cmp_lt_i32 s5, s4
	s_cbranch_scc0 .LBB0_27

.LcL_20:
	s_waitcnt lgkmcnt(0)
	s_barrier
	s_setprio 2
	ds_read_b128 v[190:193], v179 offset:36864
	ds_read_b128 v[194:197], v179 offset:41472
	ds_read_b128 v[206:209], v178
	ds_read_b128 v[216:219], v178 offset:4608
	ds_read_b128 v[236:239], v178 offset:9216
	ds_read_b128 v[240:243], v178 offset:13824
	ds_read_b128 v[244:247], v178 offset:32
	s_waitcnt lgkmcnt(4)
	v_mfma_f32_32x32x16_bf16 v[114:129], v[190:193], v[206:209], v[114:129]
	s_ashr_i32 s1, s0, 31
	s_lshl_b64 s[6:7], s[0:1], 7
	v_lshl_add_u64 v[154:155], v[180:181], 0, s[6:7]
	v_mfma_f32_32x32x16_bf16 v[98:113], v[194:197], v[206:209], v[98:113]
	v_add_co_u32_e32 v130, vcc, 0x2c000, v154
	v_lshl_add_u64 v[170:171], v[182:183], 0, s[6:7]
	s_nop 0
	ds_read_b128 v[206:209], v178 offset:4640
	ds_read_b128 v[198:201], v179 offset:36896
	ds_read_b128 v[202:205], v179 offset:41504
	s_waitcnt lgkmcnt(6)
	v_mfma_f32_32x32x16_bf16 v[82:97], v[190:193], v[216:219], v[82:97]
	v_addc_co_u32_e32 v131, vcc, 0, v155, vcc
	v_add_co_u32_e32 v134, vcc, 0x58000, v154
	global_load_dwordx4 v[142:145], v[154:155], off
	v_mfma_f32_32x32x16_bf16 v[66:81], v[194:197], v[216:219], v[66:81]
	s_nop 0
	global_load_dwordx4 v[130:133], v[130:131], off
	v_addc_co_u32_e32 v135, vcc, 0, v155, vcc
	ds_read_b128 v[216:219], v178 offset:9248
	s_waitcnt lgkmcnt(6)
	v_mfma_f32_32x32x16_bf16 v[50:65], v[190:193], v[236:239], v[50:65]
	v_add_co_u32_e32 v138, vcc, 0x84000, v154
	s_add_i32 s0, s0, 1
	s_nop 0
	v_mfma_f32_32x32x16_bf16 v[34:49], v[194:197], v[236:239], v[34:49]
	v_addc_co_u32_e32 v139, vcc, 0, v155, vcc
	v_add_co_u32_e32 v146, vcc, 0xb0000, v154
	global_load_dwordx4 v[134:137], v[134:135], off
	ds_read_b128 v[236:239], v178 offset:13856
	s_waitcnt lgkmcnt(6)
	v_mfma_f32_32x32x16_bf16 v[18:33], v[190:193], v[240:243], v[18:33]
	s_nop 0
	global_load_dwordx4 v[138:141], v[138:139], off
	v_addc_co_u32_e32 v147, vcc, 0, v155, vcc
	v_mfma_f32_32x32x16_bf16 v[2:17], v[194:197], v[240:243], v[2:17]
	v_add_co_u32_e32 v150, vcc, 0xdc000, v154
	s_nop 0
	v_addc_co_u32_e32 v151, vcc, 0, v155, vcc
	ds_read_b128 v[240:243], v178 offset:64
	s_waitcnt lgkmcnt(3)
	v_mfma_f32_32x32x16_bf16 v[114:129], v[198:201], v[244:247], v[114:129]
	v_add_co_u32_e32 v156, vcc, 0x108000, v154
	global_load_dwordx4 v[146:149], v[146:147], off
	s_nop 0
	v_mfma_f32_32x32x16_bf16 v[98:113], v[202:205], v[244:247], v[98:113]
	global_load_dwordx4 v[150:153], v[150:151], off
	v_addc_co_u32_e32 v157, vcc, 0, v155, vcc
	v_add_co_u32_e32 v158, vcc, 0x134000, v154
	ds_read_b128 v[244:247], v178 offset:4672
	ds_read_b128 v[190:193], v179 offset:36928
	ds_read_b128 v[194:197], v179 offset:41536
	v_mfma_f32_32x32x16_bf16 v[82:97], v[198:201], v[206:209], v[82:97]
	s_nop 1
	v_addc_co_u32_e32 v159, vcc, 0, v155, vcc
	v_add_co_u32_e32 v166, vcc, 0x2c000, v170
	v_mfma_f32_32x32x16_bf16 v[66:81], v[202:205], v[206:209], v[66:81]
	global_load_dwordx4 v[154:157], v[156:157], off
	s_nop 0
	global_load_dwordx4 v[158:161], v[158:159], off
	ds_read_b128 v[206:209], v178 offset:9280
	s_waitcnt lgkmcnt(6)
	v_mfma_f32_32x32x16_bf16 v[50:65], v[198:201], v[216:219], v[50:65]
	v_addc_co_u32_e32 v167, vcc, 0, v171, vcc
	v_add_co_u32_e32 v172, vcc, 0x58000, v170
	global_load_dwordx4 v[162:165], v[170:171], off
	v_mfma_f32_32x32x16_bf16 v[34:49], v[202:205], v[216:219], v[34:49]
	s_nop 0
	global_load_dwordx4 v[166:169], v[166:167], off
	v_addc_co_u32_e32 v173, vcc, 0, v171, vcc
	ds_read_b128 v[216:219], v178 offset:13888
	s_waitcnt lgkmcnt(6)
	v_mfma_f32_32x32x16_bf16 v[18:33], v[198:201], v[236:239], v[18:33]
	v_add_co_u32_e32 v174, vcc, 0x84000, v170
	s_nop 1
	v_addc_co_u32_e32 v175, vcc, 0, v171, vcc
	v_mfma_f32_32x32x16_bf16 v[2:17], v[202:205], v[236:239], v[2:17]
	global_load_dwordx4 v[170:173], v[172:173], off
	s_nop 0
	global_load_dwordx4 v[174:177], v[174:175], off
	ds_read_b128 v[236:239], v178 offset:96
	s_waitcnt lgkmcnt(3)
	v_mfma_f32_32x32x16_bf16 v[114:129], v[190:193], v[240:243], v[114:129]
	v_mfma_f32_32x32x16_bf16 v[98:113], v[194:197], v[240:243], v[98:113]
	ds_read_b128 v[240:243], v178 offset:4704
	ds_read_b128 v[198:201], v179 offset:36960
	ds_read_b128 v[202:205], v179 offset:41568
	v_mfma_f32_32x32x16_bf16 v[82:97], v[190:193], v[244:247], v[82:97]
	v_mfma_f32_32x32x16_bf16 v[66:81], v[194:197], v[244:247], v[66:81]
	ds_read_b128 v[244:247], v178 offset:9312
	s_waitcnt lgkmcnt(6)
	v_mfma_f32_32x32x16_bf16 v[50:65], v[190:193], v[206:209], v[50:65]
	v_mfma_f32_32x32x16_bf16 v[34:49], v[194:197], v[206:209], v[34:49]
	ds_read_b128 v[206:209], v178 offset:13920
	s_waitcnt lgkmcnt(6)
	v_mfma_f32_32x32x16_bf16 v[18:33], v[190:193], v[216:219], v[18:33]
	v_mfma_f32_32x32x16_bf16 v[2:17], v[194:197], v[216:219], v[2:17]
	s_waitcnt lgkmcnt(2)
	v_mfma_f32_32x32x16_bf16 v[114:129], v[198:201], v[236:239], v[114:129]
	v_mfma_f32_32x32x16_bf16 v[98:113], v[202:205], v[236:239], v[98:113]
	v_mfma_f32_32x32x16_bf16 v[82:97], v[198:201], v[240:243], v[82:97]
	v_mfma_f32_32x32x16_bf16 v[66:81], v[202:205], v[240:243], v[66:81]
	s_waitcnt lgkmcnt(1)
	v_mfma_f32_32x32x16_bf16 v[50:65], v[198:201], v[244:247], v[50:65]
	v_mfma_f32_32x32x16_bf16 v[34:49], v[202:205], v[244:247], v[34:49]
	s_waitcnt lgkmcnt(0)
	v_mfma_f32_32x32x16_bf16 v[18:33], v[198:201], v[206:209], v[18:33]
	v_mfma_f32_32x32x16_bf16 v[2:17], v[202:205], v[206:209], v[2:17]
	s_cmp_lg_u32 s0, 44
	s_setprio 0
	s_cbranch_scc1 .Ltail_20
	s_add_i32 s2, s2, 1
	s_cmp_ge_i32 s2, s4
	s_cbranch_scc1 .Lz_20
	s_mul_i32 s0, s2, s82
	s_add_i32 s0, s0, s63
	s_ashr_i32 s1, s0, 31
	s_lshr_b32 s1, s1, 28
	s_add_i32 s1, s0, s1
	s_ashr_i32 s6, s1, 4
	s_and_b32 s1, s1, -16
	s_sub_i32 s0, s0, s1
	s_lshl_b32 s1, s6, 1
	s_and_b32 s6, s0, 1
	s_or_b32 s6, s6, s1
	s_lshr_b32 s7, s0, 1
	v_readlane_b32 s0, v252, 35
	s_sub_i32 s8, 0x7f, s6
	v_readlane_b32 s1, v252, 36
	s_and_b64 s[0:1], s[0:1], exec
	s_mul_i32 s0, s7, 0x58000
	s_cselect_b32 s6, s8, s6
	s_ashr_i32 s1, s0, 31
	v_mov_b32_e32 v0, 0x160000
	v_mad_i64_i32 v[180:181], s[6:7], s6, v0, v[186:187]
	v_lshl_add_u64 v[182:183], s[0:1], 1, v[188:189]
.Lz_20:
	s_mov_b32 s0, 0
	s_branch .Ltail_20

.Ltail_34:
	s_add_i32 s3, s3, 1
	s_cmp_lg_u32 s3, 16
	s_cbranch_scc0 .LBB0_40
	s_cmp_ge_i32 s5, s4
	s_cbranch_scc1 .LBB0_41

.LcL_34:
	s_waitcnt lgkmcnt(0)
	s_barrier
	s_setprio 2
	ds_read_b128 v[190:193], v179 offset:36864
	ds_read_b128 v[194:197], v179 offset:41472
	ds_read_b128 v[206:209], v178
	ds_read_b128 v[216:219], v178 offset:4608
	ds_read_b128 v[236:239], v178 offset:9216
	ds_read_b128 v[240:243], v178 offset:13824
	ds_read_b128 v[244:247], v178 offset:32
	s_waitcnt lgkmcnt(4)
	v_mfma_f32_32x32x16_bf16 v[114:129], v[190:193], v[206:209], v[114:129]
	s_ashr_i32 s1, s0, 31
	s_lshl_b64 s[6:7], s[0:1], 7
	v_lshl_add_u64 v[154:155], v[180:181], 0, s[6:7]
	v_mfma_f32_32x32x16_bf16 v[98:113], v[194:197], v[206:209], v[98:113]
	v_add_co_u32_e32 v130, vcc, 0x10000, v154
	v_lshl_add_u64 v[170:171], v[182:183], 0, s[6:7]
	s_nop 0
	ds_read_b128 v[206:209], v178 offset:4640
	ds_read_b128 v[198:201], v179 offset:36896
	ds_read_b128 v[202:205], v179 offset:41504
	s_waitcnt lgkmcnt(6)
	v_mfma_f32_32x32x16_bf16 v[82:97], v[190:193], v[216:219], v[82:97]
	v_addc_co_u32_e32 v131, vcc, 0, v155, vcc
	v_add_co_u32_e32 v134, vcc, 0x20000, v154
	global_load_dwordx4 v[142:145], v[154:155], off
	v_mfma_f32_32x32x16_bf16 v[66:81], v[194:197], v[216:219], v[66:81]
	s_nop 0
	global_load_dwordx4 v[130:133], v[130:131], off
	v_addc_co_u32_e32 v135, vcc, 0, v155, vcc
	ds_read_b128 v[216:219], v178 offset:9248
	s_waitcnt lgkmcnt(6)
	v_mfma_f32_32x32x16_bf16 v[50:65], v[190:193], v[236:239], v[50:65]
	v_add_co_u32_e32 v138, vcc, 0x30000, v154
	s_add_i32 s0, s0, 1
	s_nop 0
	v_mfma_f32_32x32x16_bf16 v[34:49], v[194:197], v[236:239], v[34:49]
	v_addc_co_u32_e32 v139, vcc, 0, v155, vcc
	v_add_co_u32_e32 v146, vcc, 0x40000, v154
	global_load_dwordx4 v[134:137], v[134:135], off
	ds_read_b128 v[236:239], v178 offset:13856
	s_waitcnt lgkmcnt(6)
	v_mfma_f32_32x32x16_bf16 v[18:33], v[190:193], v[240:243], v[18:33]
	s_nop 0
	global_load_dwordx4 v[138:141], v[138:139], off
	v_addc_co_u32_e32 v147, vcc, 0, v155, vcc
	v_mfma_f32_32x32x16_bf16 v[2:17], v[194:197], v[240:243], v[2:17]
	v_add_co_u32_e32 v150, vcc, 0x50000, v154
	s_nop 0
	v_addc_co_u32_e32 v151, vcc, 0, v155, vcc
	ds_read_b128 v[240:243], v178 offset:64
	s_waitcnt lgkmcnt(3)
	v_mfma_f32_32x32x16_bf16 v[114:129], v[198:201], v[244:247], v[114:129]
	v_add_co_u32_e32 v156, vcc, 0x60000, v154
	global_load_dwordx4 v[146:149], v[146:147], off
	s_nop 0
	v_mfma_f32_32x32x16_bf16 v[98:113], v[202:205], v[244:247], v[98:113]
	global_load_dwordx4 v[150:153], v[150:151], off
	v_addc_co_u32_e32 v157, vcc, 0, v155, vcc
	v_add_co_u32_e32 v158, vcc, 0x70000, v154
	ds_read_b128 v[244:247], v178 offset:4672
	ds_read_b128 v[190:193], v179 offset:36928
	ds_read_b128 v[194:197], v179 offset:41536
	v_mfma_f32_32x32x16_bf16 v[82:97], v[198:201], v[206:209], v[82:97]
	s_nop 1
	v_addc_co_u32_e32 v159, vcc, 0, v155, vcc
	v_add_co_u32_e32 v166, vcc, 0x10000, v170
	v_mfma_f32_32x32x16_bf16 v[66:81], v[202:205], v[206:209], v[66:81]
	global_load_dwordx4 v[154:157], v[156:157], off
	s_nop 0
	global_load_dwordx4 v[158:161], v[158:159], off
	ds_read_b128 v[206:209], v178 offset:9280
	s_waitcnt lgkmcnt(6)
	v_mfma_f32_32x32x16_bf16 v[50:65], v[198:201], v[216:219], v[50:65]
	v_addc_co_u32_e32 v167, vcc, 0, v171, vcc
	v_add_co_u32_e32 v172, vcc, 0x20000, v170
	global_load_dwordx4 v[162:165], v[170:171], off
	v_mfma_f32_32x32x16_bf16 v[34:49], v[202:205], v[216:219], v[34:49]
	s_nop 0
	global_load_dwordx4 v[166:169], v[166:167], off
	v_addc_co_u32_e32 v173, vcc, 0, v171, vcc
	ds_read_b128 v[216:219], v178 offset:13888
	s_waitcnt lgkmcnt(6)
	v_mfma_f32_32x32x16_bf16 v[18:33], v[198:201], v[236:239], v[18:33]
	v_add_co_u32_e32 v174, vcc, 0x30000, v170
	s_nop 1
	v_addc_co_u32_e32 v175, vcc, 0, v171, vcc
	v_mfma_f32_32x32x16_bf16 v[2:17], v[202:205], v[236:239], v[2:17]
	global_load_dwordx4 v[170:173], v[172:173], off
	s_nop 0
	global_load_dwordx4 v[174:177], v[174:175], off
	ds_read_b128 v[236:239], v178 offset:96
	s_waitcnt lgkmcnt(3)
	v_mfma_f32_32x32x16_bf16 v[114:129], v[190:193], v[240:243], v[114:129]
	v_mfma_f32_32x32x16_bf16 v[98:113], v[194:197], v[240:243], v[98:113]
	ds_read_b128 v[240:243], v178 offset:4704
	ds_read_b128 v[198:201], v179 offset:36960
	ds_read_b128 v[202:205], v179 offset:41568
	v_mfma_f32_32x32x16_bf16 v[82:97], v[190:193], v[244:247], v[82:97]
	v_mfma_f32_32x32x16_bf16 v[66:81], v[194:197], v[244:247], v[66:81]
	ds_read_b128 v[244:247], v178 offset:9312
	s_waitcnt lgkmcnt(6)
	v_mfma_f32_32x32x16_bf16 v[50:65], v[190:193], v[206:209], v[50:65]
	v_mfma_f32_32x32x16_bf16 v[34:49], v[194:197], v[206:209], v[34:49]
	ds_read_b128 v[206:209], v178 offset:13920
	s_waitcnt lgkmcnt(6)
	v_mfma_f32_32x32x16_bf16 v[18:33], v[190:193], v[216:219], v[18:33]
	v_mfma_f32_32x32x16_bf16 v[2:17], v[194:197], v[216:219], v[2:17]
	s_waitcnt lgkmcnt(2)
	v_mfma_f32_32x32x16_bf16 v[114:129], v[198:201], v[236:239], v[114:129]
	v_mfma_f32_32x32x16_bf16 v[98:113], v[202:205], v[236:239], v[98:113]
	v_mfma_f32_32x32x16_bf16 v[82:97], v[198:201], v[240:243], v[82:97]
	v_mfma_f32_32x32x16_bf16 v[66:81], v[202:205], v[240:243], v[66:81]
	s_waitcnt lgkmcnt(1)
	v_mfma_f32_32x32x16_bf16 v[50:65], v[198:201], v[244:247], v[50:65]
	v_mfma_f32_32x32x16_bf16 v[34:49], v[202:205], v[244:247], v[34:49]
	s_waitcnt lgkmcnt(0)
	v_mfma_f32_32x32x16_bf16 v[18:33], v[198:201], v[206:209], v[18:33]
	v_mfma_f32_32x32x16_bf16 v[2:17], v[202:205], v[206:209], v[2:17]
	s_cmp_lg_u32 s0, 16
	s_setprio 0
	s_cbranch_scc1 .Ltail_34
	s_add_i32 s2, s2, 1
	s_cmp_ge_i32 s2, s4
	s_cbranch_scc1 .Lz_34
	s_mul_i32 s0, s2, s82
	s_add_i32 s0, s0, s63
	s_mul_hi_i32 s1, s0, 0x2e8ba2e9
	s_lshr_b32 s6, s1, 31
	s_ashr_i32 s1, s1, 4
	s_add_i32 s1, s1, s6
	s_mul_i32 s6, s1, 0x58
	s_sub_i32 s0, s0, s6
	s_lshl_b32 s1, s1, 1
	s_and_b32 s6, s0, 1
	s_or_b32 s1, s6, s1
	v_readlane_b32 s6, v252, 35
	s_ashr_i32 s0, s0, 1
	s_sub_i32 s8, 0x7f, s1
	v_readlane_b32 s7, v252, 36
	s_and_b64 s[6:7], s[6:7], exec
	s_cselect_b32 s6, s8, s1
	s_ashr_i32 s7, s6, 31
	s_ashr_i32 s1, s0, 31
	s_lshl_b64 s[6:7], s[6:7], 19
	s_lshl_b64 s[0:1], s[0:1], 18
	v_lshl_add_u64 v[180:181], v[186:187], 0, s[6:7]
	v_lshl_add_u64 v[182:183], v[188:189], 0, s[0:1]

.Ltail_62:
	s_add_i32 s3, s3, 1
	s_cmp_lg_u32 s3, 16
	s_cbranch_scc0 .LBB0_68
	s_cmp_ge_i32 s7, s6
	s_cbranch_scc1 .LBB0_69

.LcL_62:
	s_waitcnt lgkmcnt(0)
	s_barrier
	s_setprio 2
	ds_read_b128 v[190:193], v179 offset:36864
	ds_read_b128 v[194:197], v179 offset:41472
	ds_read_b128 v[206:209], v178
	ds_read_b128 v[216:219], v178 offset:4608
	ds_read_b128 v[236:239], v178 offset:9216
	ds_read_b128 v[240:243], v178 offset:13824
	ds_read_b128 v[244:247], v178 offset:32
	s_waitcnt lgkmcnt(4)
	v_mfma_f32_32x32x16_bf16 v[114:129], v[190:193], v[206:209], v[114:129]
	s_ashr_i32 s1, s0, 31
	s_lshl_b64 s[4:5], s[0:1], 7
	v_lshl_add_u64 v[154:155], v[180:181], 0, s[4:5]
	v_mfma_f32_32x32x16_bf16 v[98:113], v[194:197], v[206:209], v[98:113]
	v_add_co_u32_e32 v130, vcc, 0x10000, v154
	v_lshl_add_u64 v[170:171], v[182:183], 0, s[4:5]
	s_nop 0
	ds_read_b128 v[206:209], v178 offset:4640
	ds_read_b128 v[198:201], v179 offset:36896
	ds_read_b128 v[202:205], v179 offset:41504
	s_waitcnt lgkmcnt(6)
	v_mfma_f32_32x32x16_bf16 v[82:97], v[190:193], v[216:219], v[82:97]
	v_addc_co_u32_e32 v131, vcc, 0, v155, vcc
	v_add_co_u32_e32 v134, vcc, 0x20000, v154
	global_load_dwordx4 v[142:145], v[154:155], off
	v_mfma_f32_32x32x16_bf16 v[66:81], v[194:197], v[216:219], v[66:81]
	s_nop 0
	global_load_dwordx4 v[130:133], v[130:131], off
	v_addc_co_u32_e32 v135, vcc, 0, v155, vcc
	ds_read_b128 v[216:219], v178 offset:9248
	s_waitcnt lgkmcnt(6)
	v_mfma_f32_32x32x16_bf16 v[50:65], v[190:193], v[236:239], v[50:65]
	v_add_co_u32_e32 v138, vcc, 0x30000, v154
	s_add_i32 s0, s0, 1
	s_nop 0
	v_mfma_f32_32x32x16_bf16 v[34:49], v[194:197], v[236:239], v[34:49]
	v_addc_co_u32_e32 v139, vcc, 0, v155, vcc
	v_add_co_u32_e32 v146, vcc, 0x40000, v154
	global_load_dwordx4 v[134:137], v[134:135], off
	ds_read_b128 v[236:239], v178 offset:13856
	s_waitcnt lgkmcnt(6)
	v_mfma_f32_32x32x16_bf16 v[18:33], v[190:193], v[240:243], v[18:33]
	s_nop 0
	global_load_dwordx4 v[138:141], v[138:139], off
	v_addc_co_u32_e32 v147, vcc, 0, v155, vcc
	v_mfma_f32_32x32x16_bf16 v[2:17], v[194:197], v[240:243], v[2:17]
	v_add_co_u32_e32 v150, vcc, 0x50000, v154
	s_nop 0
	v_addc_co_u32_e32 v151, vcc, 0, v155, vcc
	ds_read_b128 v[240:243], v178 offset:64
	s_waitcnt lgkmcnt(3)
	v_mfma_f32_32x32x16_bf16 v[114:129], v[198:201], v[244:247], v[114:129]
	v_add_co_u32_e32 v156, vcc, 0x60000, v154
	global_load_dwordx4 v[146:149], v[146:147], off
	s_nop 0
	v_mfma_f32_32x32x16_bf16 v[98:113], v[202:205], v[244:247], v[98:113]
	global_load_dwordx4 v[150:153], v[150:151], off
	v_addc_co_u32_e32 v157, vcc, 0, v155, vcc
	v_add_co_u32_e32 v158, vcc, 0x70000, v154
	ds_read_b128 v[244:247], v178 offset:4672
	ds_read_b128 v[190:193], v179 offset:36928
	ds_read_b128 v[194:197], v179 offset:41536
	v_mfma_f32_32x32x16_bf16 v[82:97], v[198:201], v[206:209], v[82:97]
	s_nop 1
	v_addc_co_u32_e32 v159, vcc, 0, v155, vcc
	v_add_co_u32_e32 v166, vcc, 0x10000, v170
	v_mfma_f32_32x32x16_bf16 v[66:81], v[202:205], v[206:209], v[66:81]
	global_load_dwordx4 v[154:157], v[156:157], off
	s_nop 0
	global_load_dwordx4 v[158:161], v[158:159], off
	ds_read_b128 v[206:209], v178 offset:9280
	s_waitcnt lgkmcnt(6)
	v_mfma_f32_32x32x16_bf16 v[50:65], v[198:201], v[216:219], v[50:65]
	v_addc_co_u32_e32 v167, vcc, 0, v171, vcc
	v_add_co_u32_e32 v172, vcc, 0x20000, v170
	global_load_dwordx4 v[162:165], v[170:171], off
	v_mfma_f32_32x32x16_bf16 v[34:49], v[202:205], v[216:219], v[34:49]
	s_nop 0
	global_load_dwordx4 v[166:169], v[166:167], off
	v_addc_co_u32_e32 v173, vcc, 0, v171, vcc
	ds_read_b128 v[216:219], v178 offset:13888
	s_waitcnt lgkmcnt(6)
	v_mfma_f32_32x32x16_bf16 v[18:33], v[198:201], v[236:239], v[18:33]
	v_add_co_u32_e32 v174, vcc, 0x30000, v170
	s_nop 1
	v_addc_co_u32_e32 v175, vcc, 0, v171, vcc
	v_mfma_f32_32x32x16_bf16 v[2:17], v[202:205], v[236:239], v[2:17]
	global_load_dwordx4 v[170:173], v[172:173], off
	s_nop 0
	global_load_dwordx4 v[174:177], v[174:175], off
	ds_read_b128 v[236:239], v178 offset:96
	s_waitcnt lgkmcnt(3)
	v_mfma_f32_32x32x16_bf16 v[114:129], v[190:193], v[240:243], v[114:129]
	v_mfma_f32_32x32x16_bf16 v[98:113], v[194:197], v[240:243], v[98:113]
	ds_read_b128 v[240:243], v178 offset:4704
	ds_read_b128 v[198:201], v179 offset:36960
	ds_read_b128 v[202:205], v179 offset:41568
	v_mfma_f32_32x32x16_bf16 v[82:97], v[190:193], v[244:247], v[82:97]
	v_mfma_f32_32x32x16_bf16 v[66:81], v[194:197], v[244:247], v[66:81]
	ds_read_b128 v[244:247], v178 offset:9312
	s_waitcnt lgkmcnt(6)
	v_mfma_f32_32x32x16_bf16 v[50:65], v[190:193], v[206:209], v[50:65]
	v_mfma_f32_32x32x16_bf16 v[34:49], v[194:197], v[206:209], v[34:49]
	ds_read_b128 v[206:209], v178 offset:13920
	s_waitcnt lgkmcnt(6)
	v_mfma_f32_32x32x16_bf16 v[18:33], v[190:193], v[216:219], v[18:33]
	v_mfma_f32_32x32x16_bf16 v[2:17], v[194:197], v[216:219], v[2:17]
	s_waitcnt lgkmcnt(2)
	v_mfma_f32_32x32x16_bf16 v[114:129], v[198:201], v[236:239], v[114:129]
	v_mfma_f32_32x32x16_bf16 v[98:113], v[202:205], v[236:239], v[98:113]
	v_mfma_f32_32x32x16_bf16 v[82:97], v[198:201], v[240:243], v[82:97]
	v_mfma_f32_32x32x16_bf16 v[66:81], v[202:205], v[240:243], v[66:81]
	s_waitcnt lgkmcnt(1)
	v_mfma_f32_32x32x16_bf16 v[50:65], v[198:201], v[244:247], v[50:65]
	v_mfma_f32_32x32x16_bf16 v[34:49], v[202:205], v[244:247], v[34:49]
	s_waitcnt lgkmcnt(0)
	v_mfma_f32_32x32x16_bf16 v[18:33], v[198:201], v[206:209], v[18:33]
	v_mfma_f32_32x32x16_bf16 v[2:17], v[202:205], v[206:209], v[2:17]
	s_cmp_lg_u32 s0, 16
	s_setprio 0
	s_cbranch_scc1 .Ltail_62
	s_add_i32 s2, s2, 1
	s_cmp_ge_i32 s2, s6
	s_cbranch_scc1 .Lz_62
	s_mul_i32 s0, s2, s82
	s_add_i32 s0, s0, s63
	s_ashr_i32 s1, s0, 31
	s_lshr_b32 s1, s1, 28
	s_add_i32 s1, s0, s1
	s_ashr_i32 s4, s1, 4
	s_and_b32 s1, s1, -16
	s_sub_i32 s0, s0, s1
	s_lshl_b32 s1, s4, 1
	s_and_b32 s4, s0, 1
	s_or_b32 s1, s4, s1
	v_readlane_b32 s4, v252, 35
	s_ashr_i32 s0, s0, 1
	s_sub_i32 s8, 0x7f, s1
	v_readlane_b32 s5, v252, 36
	s_and_b64 s[4:5], s[4:5], exec
	s_cselect_b32 s4, s8, s1
	s_ashr_i32 s5, s4, 31
	s_ashr_i32 s1, s0, 31
	s_lshl_b64 s[4:5], s[4:5], 19
	s_lshl_b64 s[0:1], s[0:1], 18
	v_lshl_add_u64 v[180:181], v[186:187], 0, s[4:5]
	v_lshl_add_u64 v[182:183], v[188:189], 0, s[0:1]

.LBB0_801:
	s_waitcnt lgkmcnt(0)
	s_barrier
	s_setprio 2
	ds_read_b128 v[190:193], v179 offset:36864
	ds_read_b128 v[194:197], v179 offset:41472
	ds_read_b128 v[206:209], v178
	ds_read_b128 v[216:219], v178 offset:4608
	ds_read_b128 v[236:239], v178 offset:9216
	ds_read_b128 v[240:243], v178 offset:13824
	ds_read_b128 v[244:247], v178 offset:32
	s_waitcnt lgkmcnt(4)
	v_mfma_f32_32x32x16_bf16 v[98:113], v[190:193], v[206:209], v[98:113]
	v_mfma_f32_32x32x16_bf16 v[114:129], v[194:197], v[206:209], v[114:129]
	ds_read_b128 v[206:209], v178 offset:4640
	ds_read_b128 v[198:201], v179 offset:36896
	ds_read_b128 v[202:205], v179 offset:41504
	s_waitcnt lgkmcnt(6)
	v_mfma_f32_32x32x16_bf16 v[82:97], v[190:193], v[216:219], v[82:97]
	v_mfma_f32_32x32x16_bf16 v[66:81], v[194:197], v[216:219], v[66:81]
	ds_read_b128 v[216:219], v178 offset:9248
	s_waitcnt lgkmcnt(6)
	v_mfma_f32_32x32x16_bf16 v[50:65], v[190:193], v[236:239], v[50:65]
	v_mfma_f32_32x32x16_bf16 v[34:49], v[194:197], v[236:239], v[34:49]
	ds_read_b128 v[236:239], v178 offset:13856
	s_waitcnt lgkmcnt(6)
	v_mfma_f32_32x32x16_bf16 v[18:33], v[190:193], v[240:243], v[18:33]
	v_mfma_f32_32x32x16_bf16 v[2:17], v[194:197], v[240:243], v[2:17]
	ds_read_b128 v[240:243], v178 offset:64
	s_waitcnt lgkmcnt(3)
	v_mfma_f32_32x32x16_bf16 v[98:113], v[198:201], v[244:247], v[98:113]
	v_mfma_f32_32x32x16_bf16 v[114:129], v[202:205], v[244:247], v[114:129]
	ds_read_b128 v[244:247], v178 offset:4672
	ds_read_b128 v[190:193], v179 offset:36928
	ds_read_b128 v[194:197], v179 offset:41536
	v_mfma_f32_32x32x16_bf16 v[82:97], v[198:201], v[206:209], v[82:97]
	v_mfma_f32_32x32x16_bf16 v[66:81], v[202:205], v[206:209], v[66:81]
	ds_read_b128 v[206:209], v178 offset:9280
	s_waitcnt lgkmcnt(6)
	v_mfma_f32_32x32x16_bf16 v[50:65], v[198:201], v[216:219], v[50:65]
	v_mfma_f32_32x32x16_bf16 v[34:49], v[202:205], v[216:219], v[34:49]
	ds_read_b128 v[216:219], v178 offset:13888
	s_waitcnt lgkmcnt(6)
	v_mfma_f32_32x32x16_bf16 v[18:33], v[198:201], v[236:239], v[18:33]
	v_mfma_f32_32x32x16_bf16 v[2:17], v[202:205], v[236:239], v[2:17]
	ds_read_b128 v[236:239], v178 offset:96
	s_waitcnt lgkmcnt(3)
	v_mfma_f32_32x32x16_bf16 v[98:113], v[190:193], v[240:243], v[98:113]
	v_mfma_f32_32x32x16_bf16 v[114:129], v[194:197], v[240:243], v[114:129]
	ds_read_b128 v[240:243], v178 offset:4704
	ds_read_b128 v[198:201], v179 offset:36960
	ds_read_b128 v[202:205], v179 offset:41568
	v_mfma_f32_32x32x16_bf16 v[82:97], v[190:193], v[244:247], v[82:97]
	v_mfma_f32_32x32x16_bf16 v[66:81], v[194:197], v[244:247], v[66:81]
	ds_read_b128 v[244:247], v178 offset:9312
	s_waitcnt lgkmcnt(6)
	v_mfma_f32_32x32x16_bf16 v[50:65], v[190:193], v[206:209], v[50:65]
	v_mfma_f32_32x32x16_bf16 v[34:49], v[194:197], v[206:209], v[34:49]
	ds_read_b128 v[206:209], v178 offset:13920
	s_waitcnt lgkmcnt(6)
	v_mfma_f32_32x32x16_bf16 v[18:33], v[190:193], v[216:219], v[18:33]
	v_mfma_f32_32x32x16_bf16 v[2:17], v[194:197], v[216:219], v[2:17]
	s_waitcnt lgkmcnt(2)
	v_mfma_f32_32x32x16_bf16 v[98:113], v[198:201], v[236:239], v[98:113]
	v_mfma_f32_32x32x16_bf16 v[114:129], v[202:205], v[236:239], v[114:129]
	v_mfma_f32_32x32x16_bf16 v[82:97], v[198:201], v[240:243], v[82:97]
	v_mfma_f32_32x32x16_bf16 v[66:81], v[202:205], v[240:243], v[66:81]
	s_waitcnt lgkmcnt(1)
	v_mfma_f32_32x32x16_bf16 v[50:65], v[198:201], v[244:247], v[50:65]
	v_mfma_f32_32x32x16_bf16 v[34:49], v[202:205], v[244:247], v[34:49]
	s_waitcnt lgkmcnt(0)
	v_mfma_f32_32x32x16_bf16 v[18:33], v[198:201], v[206:209], v[18:33]
	v_mfma_f32_32x32x16_bf16 v[2:17], v[202:205], v[206:209], v[2:17]
	s_setprio 0
.Ltail_801:
	s_add_i32 s5, s5, 1
	s_cmp_lg_u32 s5, 44
	s_cbranch_scc0 .LBB0_807
	s_cmp_ge_i32 s9, s8
	s_cbranch_scc1 .LBB0_808

.LcL_801:
	s_waitcnt lgkmcnt(0)
	s_barrier
	s_setprio 2
	ds_read_b128 v[190:193], v179 offset:36864
	ds_read_b128 v[194:197], v179 offset:41472
	ds_read_b128 v[206:209], v178
	ds_read_b128 v[216:219], v178 offset:4608
	ds_read_b128 v[236:239], v178 offset:9216
	ds_read_b128 v[240:243], v178 offset:13824
	ds_read_b128 v[244:247], v178 offset:32
	s_waitcnt lgkmcnt(4)
	v_mfma_f32_32x32x16_bf16 v[98:113], v[190:193], v[206:209], v[98:113]
	s_ashr_i32 s3, s2, 31
	s_lshl_b64 s[10:11], s[2:3], 7
	v_lshl_add_u64 v[154:155], v[180:181], 0, s[10:11]
	v_mfma_f32_32x32x16_bf16 v[114:129], v[194:197], v[206:209], v[114:129]
	v_add_co_u32_e32 v130, vcc, 0x2c000, v154
	v_lshl_add_u64 v[170:171], v[182:183], 0, s[10:11]
	s_nop 0
	ds_read_b128 v[206:209], v178 offset:4640
	ds_read_b128 v[198:201], v179 offset:36896
	ds_read_b128 v[202:205], v179 offset:41504
	s_waitcnt lgkmcnt(6)
	v_mfma_f32_32x32x16_bf16 v[82:97], v[190:193], v[216:219], v[82:97]
	v_addc_co_u32_e32 v131, vcc, 0, v155, vcc
	v_add_co_u32_e32 v134, vcc, 0x58000, v154
	global_load_dwordx4 v[142:145], v[154:155], off
	v_mfma_f32_32x32x16_bf16 v[66:81], v[194:197], v[216:219], v[66:81]
	s_nop 0
	global_load_dwordx4 v[130:133], v[130:131], off
	v_addc_co_u32_e32 v135, vcc, 0, v155, vcc
	ds_read_b128 v[216:219], v178 offset:9248
	s_waitcnt lgkmcnt(6)
	v_mfma_f32_32x32x16_bf16 v[50:65], v[190:193], v[236:239], v[50:65]
	v_add_co_u32_e32 v138, vcc, 0x84000, v154
	s_add_i32 s2, s2, 1
	s_nop 0
	v_mfma_f32_32x32x16_bf16 v[34:49], v[194:197], v[236:239], v[34:49]
	v_addc_co_u32_e32 v139, vcc, 0, v155, vcc
	v_add_co_u32_e32 v146, vcc, 0xb0000, v154
	global_load_dwordx4 v[134:137], v[134:135], off
	ds_read_b128 v[236:239], v178 offset:13856
	s_waitcnt lgkmcnt(6)
	v_mfma_f32_32x32x16_bf16 v[18:33], v[190:193], v[240:243], v[18:33]
	s_nop 0
	global_load_dwordx4 v[138:141], v[138:139], off
	v_addc_co_u32_e32 v147, vcc, 0, v155, vcc
	v_mfma_f32_32x32x16_bf16 v[2:17], v[194:197], v[240:243], v[2:17]
	v_add_co_u32_e32 v150, vcc, 0xdc000, v154
	s_nop 0
	v_addc_co_u32_e32 v151, vcc, 0, v155, vcc
	ds_read_b128 v[240:243], v178 offset:64
	s_waitcnt lgkmcnt(3)
	v_mfma_f32_32x32x16_bf16 v[98:113], v[198:201], v[244:247], v[98:113]
	v_add_co_u32_e32 v156, vcc, 0x108000, v154
	global_load_dwordx4 v[146:149], v[146:147], off
	s_nop 0
	v_mfma_f32_32x32x16_bf16 v[114:129], v[202:205], v[244:247], v[114:129]
	global_load_dwordx4 v[150:153], v[150:151], off
	v_addc_co_u32_e32 v157, vcc, 0, v155, vcc
	v_add_co_u32_e32 v158, vcc, 0x134000, v154
	ds_read_b128 v[244:247], v178 offset:4672
	ds_read_b128 v[190:193], v179 offset:36928
	ds_read_b128 v[194:197], v179 offset:41536
	v_mfma_f32_32x32x16_bf16 v[82:97], v[198:201], v[206:209], v[82:97]
	s_nop 1
	v_addc_co_u32_e32 v159, vcc, 0, v155, vcc
	v_add_co_u32_e32 v166, vcc, 0x2c000, v170
	v_mfma_f32_32x32x16_bf16 v[66:81], v[202:205], v[206:209], v[66:81]
	global_load_dwordx4 v[154:157], v[156:157], off
	s_nop 0
	global_load_dwordx4 v[158:161], v[158:159], off
	ds_read_b128 v[206:209], v178 offset:9280
	s_waitcnt lgkmcnt(6)
	v_mfma_f32_32x32x16_bf16 v[50:65], v[198:201], v[216:219], v[50:65]
	v_addc_co_u32_e32 v167, vcc, 0, v171, vcc
	v_add_co_u32_e32 v172, vcc, 0x58000, v170
	global_load_dwordx4 v[162:165], v[170:171], off
	v_mfma_f32_32x32x16_bf16 v[34:49], v[202:205], v[216:219], v[34:49]
	s_nop 0
	global_load_dwordx4 v[166:169], v[166:167], off
	v_addc_co_u32_e32 v173, vcc, 0, v171, vcc
	ds_read_b128 v[216:219], v178 offset:13888
	s_waitcnt lgkmcnt(6)
	v_mfma_f32_32x32x16_bf16 v[18:33], v[198:201], v[236:239], v[18:33]
	v_add_co_u32_e32 v174, vcc, 0x84000, v170
	s_nop 1
	v_addc_co_u32_e32 v175, vcc, 0, v171, vcc
	v_mfma_f32_32x32x16_bf16 v[2:17], v[202:205], v[236:239], v[2:17]
	global_load_dwordx4 v[170:173], v[172:173], off
	s_nop 0
	global_load_dwordx4 v[174:177], v[174:175], off
	ds_read_b128 v[236:239], v178 offset:96
	s_waitcnt lgkmcnt(3)
	v_mfma_f32_32x32x16_bf16 v[98:113], v[190:193], v[240:243], v[98:113]
	v_mfma_f32_32x32x16_bf16 v[114:129], v[194:197], v[240:243], v[114:129]
	ds_read_b128 v[240:243], v178 offset:4704
	ds_read_b128 v[198:201], v179 offset:36960
	ds_read_b128 v[202:205], v179 offset:41568
	v_mfma_f32_32x32x16_bf16 v[82:97], v[190:193], v[244:247], v[82:97]
	v_mfma_f32_32x32x16_bf16 v[66:81], v[194:197], v[244:247], v[66:81]
	ds_read_b128 v[244:247], v178 offset:9312
	s_waitcnt lgkmcnt(6)
	v_mfma_f32_32x32x16_bf16 v[50:65], v[190:193], v[206:209], v[50:65]
	v_mfma_f32_32x32x16_bf16 v[34:49], v[194:197], v[206:209], v[34:49]
	ds_read_b128 v[206:209], v178 offset:13920
	s_waitcnt lgkmcnt(6)
	v_mfma_f32_32x32x16_bf16 v[18:33], v[190:193], v[216:219], v[18:33]
	v_mfma_f32_32x32x16_bf16 v[2:17], v[194:197], v[216:219], v[2:17]
	s_waitcnt lgkmcnt(2)
	v_mfma_f32_32x32x16_bf16 v[98:113], v[198:201], v[236:239], v[98:113]
	v_mfma_f32_32x32x16_bf16 v[114:129], v[202:205], v[236:239], v[114:129]
	v_mfma_f32_32x32x16_bf16 v[82:97], v[198:201], v[240:243], v[82:97]
	v_mfma_f32_32x32x16_bf16 v[66:81], v[202:205], v[240:243], v[66:81]
	s_waitcnt lgkmcnt(1)
	v_mfma_f32_32x32x16_bf16 v[50:65], v[198:201], v[244:247], v[50:65]
	v_mfma_f32_32x32x16_bf16 v[34:49], v[202:205], v[244:247], v[34:49]
	s_waitcnt lgkmcnt(0)
	v_mfma_f32_32x32x16_bf16 v[18:33], v[198:201], v[206:209], v[18:33]
	v_mfma_f32_32x32x16_bf16 v[2:17], v[202:205], v[206:209], v[2:17]
	s_cmp_lg_u32 s2, 44
	s_setprio 0
	s_cbranch_scc1 .Ltail_801
	s_add_i32 s4, s4, 1
	s_cmp_ge_i32 s4, s8
	s_cbranch_scc1 .Lz_801
	s_mul_i32 s2, s4, s82
	s_add_i32 s2, s2, s63
	s_ashr_i32 s3, s2, 31
	s_lshr_b32 s3, s3, 28
	s_add_i32 s3, s2, s3
	s_ashr_i32 s10, s3, 4
	s_and_b32 s3, s3, -16
	s_sub_i32 s2, s2, s3
	s_lshl_b32 s3, s10, 1
	s_and_b32 s10, s2, 1
	s_or_b32 s10, s10, s3
	s_lshr_b32 s11, s2, 1
	v_readlane_b32 s2, v252, 35
	s_sub_i32 s12, 0x7f, s10
	v_readlane_b32 s3, v252, 36
	s_and_b64 s[2:3], s[2:3], exec
	s_mul_i32 s2, s11, 0x58000
	s_cselect_b32 s10, s12, s10
	s_ashr_i32 s3, s2, 31
	v_mov_b32_e32 v0, 0x160000
	v_mad_i64_i32 v[180:181], s[10:11], s10, v0, v[186:187]
	v_lshl_add_u64 v[182:183], s[2:3], 1, v[188:189]
.Lz_801:
	s_mov_b32 s2, 0
	s_branch .Ltail_801

.LcL_815:
	s_waitcnt lgkmcnt(0)
	s_barrier
	s_setprio 2
	ds_read_b128 v[190:193], v179 offset:36864
	ds_read_b128 v[194:197], v179 offset:41472
	ds_read_b128 v[206:209], v178
	ds_read_b128 v[216:219], v178 offset:4608
	ds_read_b128 v[236:239], v178 offset:9216
	ds_read_b128 v[240:243], v178 offset:13824
	ds_read_b128 v[244:247], v178 offset:32
	s_waitcnt lgkmcnt(4)
	v_mfma_f32_32x32x16_bf16 v[114:129], v[190:193], v[206:209], v[114:129]
	s_ashr_i32 s1, s0, 31
	s_lshl_b64 s[8:9], s[0:1], 7
	v_lshl_add_u64 v[154:155], v[180:181], 0, s[8:9]
	v_mfma_f32_32x32x16_bf16 v[98:113], v[194:197], v[206:209], v[98:113]
	v_add_co_u32_e32 v130, vcc, 0x10000, v154
	v_lshl_add_u64 v[170:171], v[182:183], 0, s[8:9]
	s_nop 0
	ds_read_b128 v[206:209], v178 offset:4640
	ds_read_b128 v[198:201], v179 offset:36896
	ds_read_b128 v[202:205], v179 offset:41504
	s_waitcnt lgkmcnt(6)
	v_mfma_f32_32x32x16_bf16 v[82:97], v[190:193], v[216:219], v[82:97]
	v_addc_co_u32_e32 v131, vcc, 0, v155, vcc
	v_add_co_u32_e32 v134, vcc, 0x20000, v154
	global_load_dwordx4 v[142:145], v[154:155], off
	v_mfma_f32_32x32x16_bf16 v[66:81], v[194:197], v[216:219], v[66:81]
	s_nop 0
	global_load_dwordx4 v[130:133], v[130:131], off
	v_addc_co_u32_e32 v135, vcc, 0, v155, vcc
	ds_read_b128 v[216:219], v178 offset:9248
	s_waitcnt lgkmcnt(6)
	v_mfma_f32_32x32x16_bf16 v[50:65], v[190:193], v[236:239], v[50:65]
	v_add_co_u32_e32 v138, vcc, 0x30000, v154
	s_add_i32 s0, s0, 1
	s_nop 0
	v_mfma_f32_32x32x16_bf16 v[34:49], v[194:197], v[236:239], v[34:49]
	v_addc_co_u32_e32 v139, vcc, 0, v155, vcc
	v_add_co_u32_e32 v146, vcc, 0x40000, v154
	global_load_dwordx4 v[134:137], v[134:135], off
	ds_read_b128 v[236:239], v178 offset:13856
	s_waitcnt lgkmcnt(6)
	v_mfma_f32_32x32x16_bf16 v[18:33], v[190:193], v[240:243], v[18:33]
	s_nop 0
	global_load_dwordx4 v[138:141], v[138:139], off
	v_addc_co_u32_e32 v147, vcc, 0, v155, vcc
	v_mfma_f32_32x32x16_bf16 v[2:17], v[194:197], v[240:243], v[2:17]
	v_add_co_u32_e32 v150, vcc, 0x50000, v154
	s_nop 0
	v_addc_co_u32_e32 v151, vcc, 0, v155, vcc
	ds_read_b128 v[240:243], v178 offset:64
	s_waitcnt lgkmcnt(3)
	v_mfma_f32_32x32x16_bf16 v[114:129], v[198:201], v[244:247], v[114:129]
	v_add_co_u32_e32 v156, vcc, 0x60000, v154
	global_load_dwordx4 v[146:149], v[146:147], off
	s_nop 0
	v_mfma_f32_32x32x16_bf16 v[98:113], v[202:205], v[244:247], v[98:113]
	global_load_dwordx4 v[150:153], v[150:151], off
	v_addc_co_u32_e32 v157, vcc, 0, v155, vcc
	v_add_co_u32_e32 v158, vcc, 0x70000, v154
	ds_read_b128 v[244:247], v178 offset:4672
	ds_read_b128 v[190:193], v179 offset:36928
	ds_read_b128 v[194:197], v179 offset:41536
	v_mfma_f32_32x32x16_bf16 v[82:97], v[198:201], v[206:209], v[82:97]
	s_nop 1
	v_addc_co_u32_e32 v159, vcc, 0, v155, vcc
	v_add_co_u32_e32 v166, vcc, 0x10000, v170
	v_mfma_f32_32x32x16_bf16 v[66:81], v[202:205], v[206:209], v[66:81]
	global_load_dwordx4 v[154:157], v[156:157], off
	s_nop 0
	global_load_dwordx4 v[158:161], v[158:159], off
	ds_read_b128 v[206:209], v178 offset:9280
	s_waitcnt lgkmcnt(6)
	v_mfma_f32_32x32x16_bf16 v[50:65], v[198:201], v[216:219], v[50:65]
	v_addc_co_u32_e32 v167, vcc, 0, v171, vcc
	v_add_co_u32_e32 v172, vcc, 0x20000, v170
	global_load_dwordx4 v[162:165], v[170:171], off
	v_mfma_f32_32x32x16_bf16 v[34:49], v[202:205], v[216:219], v[34:49]
	s_nop 0
	global_load_dwordx4 v[166:169], v[166:167], off
	v_addc_co_u32_e32 v173, vcc, 0, v171, vcc
	ds_read_b128 v[216:219], v178 offset:13888
	s_waitcnt lgkmcnt(6)
	v_mfma_f32_32x32x16_bf16 v[18:33], v[198:201], v[236:239], v[18:33]
	v_add_co_u32_e32 v174, vcc, 0x30000, v170
	s_nop 1
	v_addc_co_u32_e32 v175, vcc, 0, v171, vcc
	v_mfma_f32_32x32x16_bf16 v[2:17], v[202:205], v[236:239], v[2:17]
	global_load_dwordx4 v[170:173], v[172:173], off
	s_nop 0
	global_load_dwordx4 v[174:177], v[174:175], off
	ds_read_b128 v[236:239], v178 offset:96
	s_waitcnt lgkmcnt(3)
	v_mfma_f32_32x32x16_bf16 v[114:129], v[190:193], v[240:243], v[114:129]
	v_mfma_f32_32x32x16_bf16 v[98:113], v[194:197], v[240:243], v[98:113]
	ds_read_b128 v[240:243], v178 offset:4704
	ds_read_b128 v[198:201], v179 offset:36960
	ds_read_b128 v[202:205], v179 offset:41568
	v_mfma_f32_32x32x16_bf16 v[82:97], v[190:193], v[244:247], v[82:97]
	v_mfma_f32_32x32x16_bf16 v[66:81], v[194:197], v[244:247], v[66:81]
	ds_read_b128 v[244:247], v178 offset:9312
	s_waitcnt lgkmcnt(6)
	v_mfma_f32_32x32x16_bf16 v[50:65], v[190:193], v[206:209], v[50:65]
	v_mfma_f32_32x32x16_bf16 v[34:49], v[194:197], v[206:209], v[34:49]
	ds_read_b128 v[206:209], v178 offset:13920
	s_waitcnt lgkmcnt(6)
	v_mfma_f32_32x32x16_bf16 v[18:33], v[190:193], v[216:219], v[18:33]
	v_mfma_f32_32x32x16_bf16 v[2:17], v[194:197], v[216:219], v[2:17]
	s_waitcnt lgkmcnt(2)
	v_mfma_f32_32x32x16_bf16 v[114:129], v[198:201], v[236:239], v[114:129]
	v_mfma_f32_32x32x16_bf16 v[98:113], v[202:205], v[236:239], v[98:113]
	v_mfma_f32_32x32x16_bf16 v[82:97], v[198:201], v[240:243], v[82:97]
	v_mfma_f32_32x32x16_bf16 v[66:81], v[202:205], v[240:243], v[66:81]
	s_waitcnt lgkmcnt(1)
	v_mfma_f32_32x32x16_bf16 v[50:65], v[198:201], v[244:247], v[50:65]
	v_mfma_f32_32x32x16_bf16 v[34:49], v[202:205], v[244:247], v[34:49]
	s_waitcnt lgkmcnt(0)
	v_mfma_f32_32x32x16_bf16 v[18:33], v[198:201], v[206:209], v[18:33]
	v_mfma_f32_32x32x16_bf16 v[2:17], v[202:205], v[206:209], v[2:17]
	s_cmp_lg_u32 s0, 16
	s_setprio 0
	s_cbranch_scc1 .Ltail_815
	s_add_i32 s2, s2, 1
	s_cmp_ge_i32 s2, s4
	s_cbranch_scc1 .Lz_815
	s_mul_i32 s0, s2, s82
	s_add_i32 s0, s0, s63
	s_mul_hi_i32 s1, s0, 0x2e8ba2e9
	s_lshr_b32 s8, s1, 31
	s_ashr_i32 s1, s1, 4
	s_add_i32 s1, s1, s8
	s_mul_i32 s8, s1, 0x58
	s_sub_i32 s0, s0, s8
	s_lshl_b32 s1, s1, 1
	s_and_b32 s8, s0, 1
	s_or_b32 s1, s8, s1
	v_readlane_b32 s8, v252, 35
	s_ashr_i32 s0, s0, 1
	s_sub_i32 s10, 0x7f, s1
	v_readlane_b32 s9, v252, 36
	s_and_b64 s[8:9], s[8:9], exec
	s_cselect_b32 s8, s10, s1
	s_ashr_i32 s9, s8, 31
	s_ashr_i32 s1, s0, 31
	s_lshl_b64 s[8:9], s[8:9], 19
	s_lshl_b64 s[0:1], s[0:1], 18
	v_lshl_add_u64 v[180:181], v[186:187], 0, s[8:9]
	v_lshl_add_u64 v[182:183], v[188:189], 0, s[0:1]
